# fourier_out: in-loop weight batches issued one batch ahead into dedicated registers (removes 4 exposed L2 round trips per item)
# baseline (speedup 1.0000x reference)
.LBB0_362:
	global_load_dwordx4 v[104:107], v[80:81], off
	global_load_dwordx4 v[116:119], v[80:81], off offset:2048
	global_load_dwordx4 v[120:123], v[82:83], off
	global_load_dwordx4 v[132:135], v[84:85], off
	s_ashr_i32 s11, s3, 31
	s_lshr_b32 s11, s11, 19
	s_add_i32 s11, s3, s11
	s_and_b32 s11, s11, 0xffffe000
	s_sub_i32 s11, s3, s11
	v_or_b32_e32 v0, s11, v158
	s_ashr_i32 s11, s0, 31
	s_lshr_b32 s11, s11, 23
	s_add_i32 s11, s0, s11
	s_ashr_i32 s11, s11, 9
	s_mul_i32 s18, s11, 0x84
	s_ashr_i32 s19, s18, 31
	v_sub_u32_e32 v1, 0, v0
	s_lshl_b64 s[18:19], s[18:19], 15
	v_and_b32_e32 v2, 0x1fff, v1
	v_ashrrev_i32_e32 v1, 31, v0
	s_add_u32 s22, s16, s18
	s_addc_u32 s23, s33, s19
	v_lshlrev_b64 v[56:57], 2, v[0:1]
	v_lshl_add_u64 v[22:23], s[22:23], 0, v[56:57]
	v_lshlrev_b32_e32 v208, 2, v2
	v_lshl_add_u64 v[0:1], v[22:23], 0, v[64:65]
	v_lshl_add_u64 v[2:3], v[22:23], 0, v[66:67]
	v_lshl_add_u64 v[4:5], v[22:23], 0, v[68:69]
	v_lshl_add_u64 v[6:7], v[22:23], 0, v[70:71]
	v_lshl_add_u64 v[8:9], v[22:23], 0, v[72:73]
	v_lshl_add_u64 v[10:11], v[22:23], 0, v[74:75]
	v_lshl_add_u64 v[12:13], v[22:23], 0, v[76:77]
	v_lshl_add_u64 v[14:15], v[22:23], 0, v[78:79]
	global_load_dword v2, v[2:3], off
	s_nop 0
	global_load_dword v0, v[0:1], off
	s_nop 0
	global_load_dword v1, v[6:7], off
	global_load_dword v3, v[4:5], off
	s_nop 0
	global_load_dword v4, v[10:11], off
	global_load_dword v5, v[8:9], off
	global_load_dword v6, v[14:15], off
	global_load_dword v7, v[12:13], off
	v_lshl_add_u64 v[20:21], s[22:23], 0, v[208:209]
	v_lshl_add_u64 v[24:25], v[20:21], 0, v[94:95]
	v_lshl_add_u64 v[26:27], v[20:21], 0, v[96:97]
	v_lshl_add_u64 v[28:29], v[20:21], 0, v[98:99]
	v_lshl_add_u64 v[30:31], v[20:21], 0, v[100:101]
	s_add_u32 s18, s22, 0x108000
	s_addc_u32 s19, s23, 0
	v_lshl_add_u64 v[38:39], s[18:19], 0, v[56:57]
	v_lshl_add_u64 v[36:37], s[18:19], 0, v[208:209]
	v_lshl_add_u64 v[40:41], v[36:37], 0, v[94:95]
	v_lshl_add_u64 v[42:43], v[36:37], 0, v[96:97]
	v_lshl_add_u64 v[44:45], v[36:37], 0, v[98:99]
	v_lshl_add_u64 v[46:47], v[36:37], 0, v[100:101]
	s_add_u32 s18, s22, 0x210000
	s_addc_u32 s19, s23, 0
	v_lshl_add_u64 v[54:55], s[18:19], 0, v[56:57]
	v_lshl_add_u64 v[52:53], s[18:19], 0, v[208:209]
	v_lshl_add_u64 v[58:59], v[52:53], 0, v[94:95]
	v_lshl_add_u64 v[60:61], v[52:53], 0, v[96:97]
	v_lshl_add_u64 v[62:63], v[52:53], 0, v[98:99]
	v_lshl_add_u64 v[160:161], v[52:53], 0, v[100:101]
	s_add_u32 s18, s22, 0x318000
	s_addc_u32 s19, s23, 0
	v_lshl_add_u64 v[166:167], s[18:19], 0, v[56:57]
	v_lshl_add_u64 v[56:57], v[166:167], 0, v[72:73]
	v_lshl_add_u64 v[164:165], s[18:19], 0, v[208:209]
	v_lshl_add_u64 v[168:169], v[164:165], 0, v[94:95]
	v_lshl_add_u64 v[170:171], v[164:165], 0, v[96:97]
	v_lshl_add_u64 v[172:173], v[164:165], 0, v[98:99]
	v_lshl_add_u64 v[174:175], v[164:165], 0, v[100:101]
	s_mov_b64 s[18:19], 0x1a000400
	s_add_i32 s0, s0, s2
	s_waitcnt vmcnt(6)
	v_cvt_pk_bf16_f32 v0, v0, v2
	s_waitcnt vmcnt(4)
	v_cvt_pk_bf16_f32 v1, v3, v1
	s_waitcnt vmcnt(2)
	v_cvt_pk_bf16_f32 v2, v5, v4
	s_waitcnt vmcnt(0)
	v_cvt_pk_bf16_f32 v3, v7, v6
	s_waitcnt vmcnt(3)
	v_mfma_f32_16x16x32_bf16 v[4:7], v[104:107], v[0:3], 0
	s_waitcnt vmcnt(2)
	v_mfma_f32_16x16x32_bf16 v[8:11], v[116:119], v[0:3], 0
	s_waitcnt vmcnt(1)
	v_mfma_f32_16x16x32_bf16 v[12:15], v[120:123], v[0:3], 0
	s_waitcnt vmcnt(0)
	v_mfma_f32_16x16x32_bf16 v[0:3], v[132:135], v[0:3], 0
	global_load_dwordx4 v[104:107], v[112:113], off
	global_load_dwordx4 v[116:119], v[108:109], off
	global_load_dwordx4 v[120:123], v[110:111], off
	global_load_dwordx4 v[132:135], v[114:115], off
	v_lshl_add_u64 v[16:17], v[22:23], 0, v[88:89]
	v_lshl_add_u64 v[18:19], v[20:21], 0, v[86:87]
	v_cndmask_b32_e32 v17, v19, v17, vcc
	v_cndmask_b32_e32 v16, v18, v16, vcc
	v_lshl_add_u64 v[18:19], v[20:21], 0, v[90:91]
	v_lshl_add_u64 v[22:23], v[20:21], 0, v[92:93]
	v_lshl_add_u64 v[20:21], v[20:21], 0, v[102:103]
	global_load_dword v16, v[16:17], off
	s_nop 0
	global_load_dword v17, v[18:19], off
	s_nop 0
	global_load_dword v18, v[24:25], off
	global_load_dword v19, v[22:23], off
	s_nop 0
	global_load_dword v22, v[28:29], off
	global_load_dword v23, v[26:27], off
	s_nop 0
	global_load_dword v20, v[20:21], off
	s_nop 0
	global_load_dword v21, v[30:31], off
	v_lshl_add_u64 v[28:29], v[38:39], 0, v[76:77]
	v_lshl_add_u64 v[30:31], v[38:39], 0, v[78:79]
	s_waitcnt vmcnt(6)
	v_cvt_pk_bf16_f32 v16, v16, v17
	s_waitcnt vmcnt(4)
	v_cvt_pk_bf16_f32 v17, v19, v18
	s_waitcnt vmcnt(2)
	v_cvt_pk_bf16_f32 v18, v23, v22
	s_waitcnt vmcnt(0)
	v_cvt_pk_bf16_f32 v19, v21, v20
	s_waitcnt vmcnt(0)
	v_mfma_f32_16x16x32_bf16 v[24:27], v[176:179], v[16:19], v[4:7]
	s_nop 2
	v_lshl_add_u64 v[20:21], v[38:39], 0, v[72:73]
	v_lshl_add_u64 v[22:23], v[38:39], 0, v[74:75]
	s_waitcnt vmcnt(0)
	v_mfma_f32_16x16x32_bf16 v[8:11], v[180:183], v[16:19], v[8:11]
	s_waitcnt vmcnt(0)
	v_mfma_f32_16x16x32_bf16 v[4:7], v[184:187], v[16:19], v[12:15]
	s_nop 2
	s_waitcnt vmcnt(0)
	v_mfma_f32_16x16x32_bf16 v[0:3], v[188:191], v[16:19], v[0:3]
	v_lshl_add_u64 v[12:13], v[38:39], 0, v[64:65]
	v_lshl_add_u64 v[14:15], v[38:39], 0, v[66:67]
	v_lshl_add_u64 v[16:17], v[38:39], 0, v[68:69]
	v_lshl_add_u64 v[18:19], v[38:39], 0, v[70:71]
	global_load_dword v14, v[14:15], off
	s_nop 0
	global_load_dword v12, v[12:13], off
	s_nop 0
	global_load_dword v13, v[18:19], off
	global_load_dword v15, v[16:17], off
	s_nop 0
	global_load_dword v16, v[22:23], off
	global_load_dword v17, v[20:21], off
	global_load_dword v18, v[30:31], off
	global_load_dword v19, v[28:29], off
	s_waitcnt vmcnt(6)
	v_cvt_pk_bf16_f32 v12, v12, v14
	s_waitcnt vmcnt(4)
	v_cvt_pk_bf16_f32 v13, v15, v13
	s_waitcnt vmcnt(2)
	v_cvt_pk_bf16_f32 v14, v17, v16
	s_waitcnt vmcnt(0)
	v_cvt_pk_bf16_f32 v15, v19, v18
	s_waitcnt vmcnt(2)
	v_mfma_f32_16x16x32_bf16 v[32:35], v[104:107], v[12:15], 0
	s_waitcnt vmcnt(2)
	v_mfma_f32_16x16x32_bf16 v[16:19], v[116:119], v[12:15], 0
	s_waitcnt vmcnt(1)
	v_mfma_f32_16x16x32_bf16 v[20:23], v[120:123], v[12:15], 0
	s_waitcnt vmcnt(0)
	v_mfma_f32_16x16x32_bf16 v[12:15], v[132:135], v[12:15], 0
	global_load_dwordx4 v[104:107], v[128:129], off
	global_load_dwordx4 v[116:119], v[124:125], off
	global_load_dwordx4 v[120:123], v[126:127], off
	global_load_dwordx4 v[132:135], v[130:131], off
	v_lshl_add_u64 v[28:29], v[38:39], 0, v[88:89]
	v_lshl_add_u64 v[30:31], v[36:37], 0, v[86:87]
	v_cndmask_b32_e32 v29, v31, v29, vcc
	v_cndmask_b32_e32 v28, v30, v28, vcc
	v_lshl_add_u64 v[30:31], v[36:37], 0, v[90:91]
	v_lshl_add_u64 v[38:39], v[36:37], 0, v[92:93]
	v_lshl_add_u64 v[36:37], v[36:37], 0, v[102:103]
	global_load_dword v28, v[28:29], off
	s_nop 0
	global_load_dword v29, v[30:31], off
	s_nop 0
	global_load_dword v30, v[40:41], off
	global_load_dword v31, v[38:39], off
	s_nop 0
	global_load_dword v38, v[44:45], off
	global_load_dword v39, v[42:43], off
	global_load_dword v40, v[36:37], off
	global_load_dword v41, v[46:47], off
	v_lshl_add_u64 v[42:43], v[54:55], 0, v[74:75]
	v_lshl_add_u64 v[44:45], v[54:55], 0, v[76:77]
	v_lshl_add_u64 v[46:47], v[54:55], 0, v[78:79]
	s_waitcnt vmcnt(6)
	v_cvt_pk_bf16_f32 v36, v28, v29
	s_waitcnt vmcnt(4)
	v_cvt_pk_bf16_f32 v37, v31, v30
	s_waitcnt vmcnt(2)
	v_cvt_pk_bf16_f32 v38, v39, v38
	s_waitcnt vmcnt(0)
	v_cvt_pk_bf16_f32 v39, v41, v40
	v_lshl_add_u64 v[40:41], v[54:55], 0, v[72:73]
	s_waitcnt vmcnt(0)
	v_mfma_f32_16x16x32_bf16 v[28:31], v[192:195], v[36:39], v[16:19]
	s_nop 2
	s_waitcnt vmcnt(0)
	v_mfma_f32_16x16x32_bf16 v[20:23], v[196:199], v[36:39], v[20:23]
	s_waitcnt vmcnt(0)
	v_mfma_f32_16x16x32_bf16 v[16:19], v[200:203], v[36:39], v[32:35]
	s_nop 2
	s_waitcnt vmcnt(0)
	v_mfma_f32_16x16x32_bf16 v[12:15], v[204:207], v[36:39], v[12:15]
	v_lshl_add_u64 v[32:33], v[54:55], 0, v[64:65]
	v_lshl_add_u64 v[34:35], v[54:55], 0, v[66:67]
	v_lshl_add_u64 v[36:37], v[54:55], 0, v[68:69]
	v_lshl_add_u64 v[38:39], v[54:55], 0, v[70:71]
	global_load_dword v34, v[34:35], off
	s_nop 0
	global_load_dword v32, v[32:33], off
	s_nop 0
	global_load_dword v33, v[38:39], off
	global_load_dword v35, v[36:37], off
	s_nop 0
	global_load_dword v36, v[42:43], off
	global_load_dword v37, v[40:41], off
	global_load_dword v38, v[46:47], off
	global_load_dword v39, v[44:45], off
	s_waitcnt vmcnt(6)
	v_cvt_pk_bf16_f32 v32, v32, v34
	s_waitcnt vmcnt(4)
	v_cvt_pk_bf16_f32 v33, v35, v33
	s_waitcnt vmcnt(2)
	v_cvt_pk_bf16_f32 v34, v37, v36
	s_waitcnt vmcnt(0)
	v_cvt_pk_bf16_f32 v35, v39, v38
	s_waitcnt vmcnt(2)
	v_mfma_f32_16x16x32_bf16 v[48:51], v[104:107], v[32:35], 0
	s_waitcnt vmcnt(2)
	v_mfma_f32_16x16x32_bf16 v[36:39], v[116:119], v[32:35], 0
	s_waitcnt vmcnt(1)
	v_mfma_f32_16x16x32_bf16 v[40:43], v[120:123], v[32:35], 0
	s_waitcnt vmcnt(0)
	v_mfma_f32_16x16x32_bf16 v[32:35], v[132:135], v[32:35], 0
	global_load_dwordx4 v[104:107], v[144:145], off
	global_load_dwordx4 v[116:119], v[140:141], off
	global_load_dwordx4 v[120:123], v[142:143], off
	global_load_dwordx4 v[132:135], v[146:147], off
	v_lshl_add_u64 v[44:45], v[54:55], 0, v[88:89]
	v_lshl_add_u64 v[46:47], v[52:53], 0, v[86:87]
	v_cndmask_b32_e32 v45, v47, v45, vcc
	v_cndmask_b32_e32 v44, v46, v44, vcc
	v_lshl_add_u64 v[46:47], v[52:53], 0, v[90:91]
	v_lshl_add_u64 v[54:55], v[52:53], 0, v[92:93]
	v_lshl_add_u64 v[52:53], v[52:53], 0, v[102:103]
	global_load_dword v44, v[44:45], off
	s_nop 0
	global_load_dword v45, v[46:47], off
	s_nop 0
	global_load_dword v46, v[58:59], off
	global_load_dword v47, v[54:55], off
	s_nop 0
	global_load_dword v54, v[62:63], off
	global_load_dword v55, v[60:61], off
	global_load_dword v58, v[52:53], off
	global_load_dword v59, v[160:161], off
	v_lshl_add_u64 v[60:61], v[166:167], 0, v[76:77]
	v_lshl_add_u64 v[62:63], v[166:167], 0, v[78:79]
	s_waitcnt vmcnt(6)
	v_cvt_pk_bf16_f32 v52, v44, v45
	s_waitcnt vmcnt(4)
	v_cvt_pk_bf16_f32 v53, v47, v46
	s_waitcnt vmcnt(2)
	v_cvt_pk_bf16_f32 v54, v55, v54
	s_waitcnt vmcnt(0)
	v_cvt_pk_bf16_f32 v55, v59, v58
	v_lshl_add_u64 v[58:59], v[166:167], 0, v[74:75]
	s_waitcnt vmcnt(0)
	v_mfma_f32_16x16x32_bf16 v[44:47], v[214:217], v[52:55], v[36:39]
	s_nop 2
	s_waitcnt vmcnt(0)
	v_mfma_f32_16x16x32_bf16 v[40:43], v[218:221], v[52:55], v[40:43]
	s_waitcnt vmcnt(0)
	v_mfma_f32_16x16x32_bf16 v[36:39], v[222:225], v[52:55], v[48:51]
	s_nop 2
	s_waitcnt vmcnt(0)
	v_mfma_f32_16x16x32_bf16 v[32:35], v[226:229], v[52:55], v[32:35]
	v_lshl_add_u64 v[48:49], v[166:167], 0, v[64:65]
	v_lshl_add_u64 v[50:51], v[166:167], 0, v[66:67]
	v_lshl_add_u64 v[52:53], v[166:167], 0, v[68:69]
	v_lshl_add_u64 v[54:55], v[166:167], 0, v[70:71]
	global_load_dword v50, v[50:51], off
	s_nop 0
	global_load_dword v48, v[48:49], off
	s_nop 0
	global_load_dword v49, v[54:55], off
	global_load_dword v51, v[52:53], off
	s_nop 0
	global_load_dword v52, v[58:59], off
	global_load_dword v53, v[56:57], off
	global_load_dword v54, v[62:63], off
	global_load_dword v55, v[60:61], off
	s_waitcnt vmcnt(6)
	v_cvt_pk_bf16_f32 v48, v48, v50
	s_waitcnt vmcnt(4)
	v_cvt_pk_bf16_f32 v49, v51, v49
	s_waitcnt vmcnt(2)
	v_cvt_pk_bf16_f32 v50, v53, v52
	s_waitcnt vmcnt(0)
	v_cvt_pk_bf16_f32 v51, v55, v54
	s_waitcnt vmcnt(2)
	v_mfma_f32_16x16x32_bf16 v[160:163], v[104:107], v[48:51], 0
	s_waitcnt vmcnt(2)
	v_mfma_f32_16x16x32_bf16 v[52:55], v[116:119], v[48:51], 0
	s_waitcnt vmcnt(1)
	v_mfma_f32_16x16x32_bf16 v[56:59], v[120:123], v[48:51], 0
	s_waitcnt vmcnt(0)
	v_mfma_f32_16x16x32_bf16 v[48:51], v[132:135], v[48:51], 0
	v_lshl_add_u64 v[60:61], v[166:167], 0, v[88:89]
	v_lshl_add_u64 v[62:63], v[164:165], 0, v[86:87]
	v_cndmask_b32_e32 v61, v63, v61, vcc
	v_cndmask_b32_e32 v60, v62, v60, vcc
	v_lshl_add_u64 v[62:63], v[164:165], 0, v[90:91]
	v_lshl_add_u64 v[166:167], v[164:165], 0, v[92:93]
	v_lshl_add_u64 v[164:165], v[164:165], 0, v[102:103]
	global_load_dword v60, v[60:61], off
	s_nop 0
	global_load_dword v61, v[62:63], off
	s_nop 0
	global_load_dword v62, v[168:169], off
	global_load_dword v63, v[166:167], off
	global_load_dword v157, v[172:173], off
	global_load_dword v159, v[170:171], off
	s_nop 0
	global_load_dword v167, v[164:165], off
	global_load_dword v168, v[174:175], off
	s_waitcnt vmcnt(6)
	v_cvt_pk_bf16_f32 v164, v60, v61
	s_waitcnt vmcnt(4)
	v_cvt_pk_bf16_f32 v165, v63, v62
	s_waitcnt vmcnt(2)
	v_cvt_pk_bf16_f32 v166, v159, v157
	s_waitcnt vmcnt(0)
	v_cvt_pk_bf16_f32 v167, v168, v167
	v_mul_f32_e32 v157, v0, v0
	v_mul_f32_e32 v159, v1, v1
	s_waitcnt vmcnt(0)
	v_mfma_f32_16x16x32_bf16 v[60:63], v[230:233], v[164:167], v[52:55]
	s_nop 2
	s_waitcnt vmcnt(0)
	v_mfma_f32_16x16x32_bf16 v[56:59], v[234:237], v[164:167], v[56:59]
	s_waitcnt vmcnt(0)
	v_mfma_f32_16x16x32_bf16 v[52:55], v[238:241], v[164:167], v[160:163]
	s_nop 2
	s_waitcnt vmcnt(0)
	v_mfma_f32_16x16x32_bf16 v[48:51], v[246:249], v[164:167], v[48:51]
	v_mul_f32_e64 v160, v26, v26
	v_mul_f32_e64 v161, v27, v27
	v_pk_mul_f32 v[162:163], v[24:25], v[24:25]
	s_nop 0
	v_pk_mov_b32 v[164:165], v[162:163], v[160:161] op_sel:[1,0]
	v_mov_b32_e32 v163, v161
	v_pk_add_f32 v[160:161], v[164:165], v[162:163]
	v_pk_mul_f32 v[162:163], v[10:11], v[10:11]
	v_pk_mul_f32 v[164:165], v[8:9], v[8:9]
	v_pk_add_f32 v[160:161], v[160:161], v[160:161] op_sel:[0,1] op_sel_hi:[1,0]
	v_pk_mov_b32 v[166:167], v[164:165], v[162:163] op_sel:[1,0]
	v_mov_b32_e32 v165, v163
	v_pk_add_f32 v[162:163], v[166:167], v[164:165]
	v_mov_b32_e32 v161, v157
	v_pk_add_f32 v[162:163], v[162:163], v[162:163] op_sel:[0,1] op_sel_hi:[1,0]
	v_mul_f32_e32 v164, v2, v2
	v_mov_b32_e32 v163, v159
	v_pk_add_f32 v[160:161], v[160:161], v[162:163]
	v_mul_f32_e32 v162, v5, v5
	v_pk_fma_f32 v[162:163], v[4:5], v[4:5], v[162:163] op_sel_hi:[1,1,0]
	v_mul_f32_e32 v166, v3, v3
	v_mov_b32_e32 v163, v164
	v_mul_f32_e32 v164, v7, v7
	v_pk_fma_f32 v[164:165], v[6:7], v[6:7], v[164:165] op_sel_hi:[1,1,0]
	v_mul_f32_e32 v157, v16, v16
	v_mov_b32_e32 v165, v166
	v_pk_add_f32 v[162:163], v[162:163], v[164:165]
	v_pk_mul_f32 v[164:165], v[28:29], v[28:29]
	v_pk_add_f32 v[160:161], v[160:161], v[162:163]
	v_pk_mul_f32 v[162:163], v[30:31], v[30:31]
	v_mul_f32_e32 v159, v17, v17
	v_pk_mov_b32 v[166:167], v[164:165], v[162:163] op_sel:[1,0]
	v_mov_b32_e32 v165, v163
	v_pk_add_f32 v[162:163], v[166:167], v[164:165]
	v_pk_add_f32 v[160:161], v[160:161], v[160:161] op_sel:[0,1] op_sel_hi:[1,0]
	v_pk_add_f32 v[162:163], v[162:163], v[162:163] op_sel:[0,1] op_sel_hi:[1,0]
	v_mov_b32_e32 v161, v157
	v_mov_b32_e32 v163, v159
	v_pk_add_f32 v[160:161], v[160:161], v[162:163]
	v_mul_f32_e32 v162, v21, v21
	v_mul_f32_e32 v164, v18, v18
	v_pk_fma_f32 v[162:163], v[20:21], v[20:21], v[162:163] op_sel_hi:[1,1,0]
	v_mul_f32_e32 v166, v19, v19
	v_mov_b32_e32 v163, v164
	v_mul_f32_e32 v164, v23, v23
	v_pk_fma_f32 v[164:165], v[22:23], v[22:23], v[164:165] op_sel_hi:[1,1,0]
	v_mul_f32_e32 v157, v40, v40
	v_mov_b32_e32 v165, v166
	v_pk_add_f32 v[162:163], v[162:163], v[164:165]
	v_pk_mul_f32 v[164:165], v[12:13], v[12:13]
	v_pk_add_f32 v[160:161], v[160:161], v[162:163]
	v_pk_mul_f32 v[162:163], v[14:15], v[14:15]
	v_mul_f32_e32 v159, v41, v41
	v_pk_mov_b32 v[166:167], v[164:165], v[162:163] op_sel:[1,0]
	v_mov_b32_e32 v165, v163
	v_pk_add_f32 v[162:163], v[166:167], v[164:165]
	v_pk_add_f32 v[160:161], v[160:161], v[160:161] op_sel:[0,1] op_sel_hi:[1,0]
	v_pk_add_f32 v[162:163], v[162:163], v[162:163] op_sel:[0,1] op_sel_hi:[1,0]
	v_mov_b32_e32 v161, v157
	v_mov_b32_e32 v163, v159
	v_pk_add_f32 v[160:161], v[160:161], v[162:163]
	v_mul_f32_e32 v162, v45, v45
	v_mul_f32_e32 v164, v42, v42
	v_pk_fma_f32 v[162:163], v[44:45], v[44:45], v[162:163] op_sel_hi:[1,1,0]
	v_mul_f32_e32 v166, v43, v43
	v_mov_b32_e32 v163, v164
	v_mul_f32_e32 v164, v47, v47
	v_pk_fma_f32 v[164:165], v[46:47], v[46:47], v[164:165] op_sel_hi:[1,1,0]
	v_mul_f32_e32 v157, v60, v60
	v_mov_b32_e32 v165, v166
	v_pk_add_f32 v[162:163], v[162:163], v[164:165]
	v_pk_mul_f32 v[164:165], v[36:37], v[36:37]
	v_pk_add_f32 v[160:161], v[160:161], v[162:163]
	v_pk_mul_f32 v[162:163], v[38:39], v[38:39]
	v_mul_f32_e32 v159, v61, v61
	v_pk_mov_b32 v[166:167], v[164:165], v[162:163] op_sel:[1,0]
	v_mov_b32_e32 v165, v163
	v_pk_add_f32 v[162:163], v[166:167], v[164:165]
	v_pk_add_f32 v[160:161], v[160:161], v[160:161] op_sel:[0,1] op_sel_hi:[1,0]
	v_pk_add_f32 v[162:163], v[162:163], v[162:163] op_sel:[0,1] op_sel_hi:[1,0]
	v_mov_b32_e32 v161, v157
	v_mov_b32_e32 v163, v159
	v_pk_add_f32 v[160:161], v[160:161], v[162:163]
	v_mul_f32_e32 v162, v33, v33
	v_mul_f32_e32 v164, v62, v62
	v_pk_fma_f32 v[162:163], v[32:33], v[32:33], v[162:163] op_sel_hi:[1,1,0]
	v_mul_f32_e32 v166, v63, v63
	v_mov_b32_e32 v163, v164
	v_mul_f32_e32 v164, v35, v35
	v_pk_fma_f32 v[164:165], v[34:35], v[34:35], v[164:165] op_sel_hi:[1,1,0]
	v_mul_f32_e32 v157, v48, v48
	v_mov_b32_e32 v165, v166
	v_pk_add_f32 v[162:163], v[162:163], v[164:165]
	v_pk_mul_f32 v[164:165], v[56:57], v[56:57]
	v_pk_add_f32 v[160:161], v[160:161], v[162:163]
	v_pk_mul_f32 v[162:163], v[58:59], v[58:59]
	v_mul_f32_e32 v159, v49, v49
	v_pk_mov_b32 v[166:167], v[164:165], v[162:163] op_sel:[1,0]
	v_mov_b32_e32 v165, v163
	v_pk_add_f32 v[162:163], v[166:167], v[164:165]
	v_pk_add_f32 v[160:161], v[160:161], v[160:161] op_sel:[0,1] op_sel_hi:[1,0]
	v_pk_add_f32 v[162:163], v[162:163], v[162:163] op_sel:[0,1] op_sel_hi:[1,0]
	v_mov_b32_e32 v161, v157
	v_mov_b32_e32 v163, v159
	v_pk_add_f32 v[160:161], v[160:161], v[162:163]
	v_mul_f32_e32 v162, v53, v53
	v_mul_f32_e32 v164, v50, v50
	v_pk_fma_f32 v[162:163], v[52:53], v[52:53], v[162:163] op_sel_hi:[1,1,0]
	v_mul_f32_e32 v166, v51, v51
	v_mov_b32_e32 v163, v164
	v_mul_f32_e32 v164, v55, v55
	v_pk_fma_f32 v[164:165], v[54:55], v[54:55], v[164:165] op_sel_hi:[1,1,0]
	v_xor_b32_e32 v159, 16, v245
	v_mov_b32_e32 v165, v166
	v_pk_add_f32 v[162:163], v[162:163], v[164:165]
	s_nop 0
	v_pk_add_f32 v[160:161], v[160:161], v[162:163]
	s_nop 0
	v_add_f32_e32 v157, v160, v161
	v_and_b32_e32 v160, 64, v245
	v_add_u32_e32 v160, 64, v160
	v_cmp_lt_i32_e64 s[36:37], v159, v160
	s_nop 1
	v_cndmask_b32_e64 v159, v245, v159, s[36:37]
	v_lshlrev_b32_e32 v159, 2, v159
	ds_bpermute_b32 v159, v159, v157
	s_waitcnt lgkmcnt(0)
	v_add_f32_e32 v157, v157, v159
	v_xor_b32_e32 v159, 32, v245
	v_cmp_lt_i32_e64 s[36:37], v159, v160
	v_add_u32_e32 v160, s3, v158
	v_ashrrev_i32_e32 v161, 31, v160
	v_cndmask_b32_e64 v159, v245, v159, s[36:37]
	v_lshlrev_b32_e32 v159, 2, v159
	ds_bpermute_b32 v159, v159, v157
	v_lshlrev_b64 v[160:161], 11, v[160:161]
	v_lshl_add_u64 v[160:161], s[84:85], 0, v[160:161]
	s_add_i32 s3, s3, s9
	s_cmpk_lt_i32 s0, 0x1000
	s_waitcnt lgkmcnt(0)
	v_add_f32_e32 v157, v157, v159
	v_fmamk_f32 v157, v157, 0x3b800000, v244
	v_cmp_gt_f32_e64 s[36:37], s7, v157
	v_mul_f32_e32 v159, 0x4b800000, v157
	s_nop 0
	v_cndmask_b32_e64 v157, v157, v159, s[36:37]
	v_rsq_f32_e32 v157, v157
	s_nop 0
	v_mul_f32_e32 v159, 0x45800000, v157
	v_cndmask_b32_e64 v159, v157, v159, s[36:37]
	v_mov_b32_e32 v157, v209
	v_mul_f32_e32 v24, v24, v159
	v_mul_f32_e32 v25, v25, v159
	v_lshl_add_u64 v[160:161], v[160:161], 0, v[156:157]
	v_cvt_pk_bf16_f32 v24, v24, v25
	v_mul_f32_e32 v25, v26, v159
	v_mul_f32_e32 v26, v27, v159
	v_cvt_pk_bf16_f32 v25, v25, v26
	v_add_co_u32_e64 v26, s[36:37], s47, v160
	v_mul_f32_e32 v8, v8, v159
	s_nop 0
	v_addc_co_u32_e64 v27, s[36:37], 0, v161, s[36:37]
	v_mul_f32_e32 v9, v9, v159
	v_lshl_add_u64 v[162:163], v[160:161], 0, s[18:19]
	global_store_dwordx2 v[26:27], v[24:25], off offset:1024
	v_cvt_pk_bf16_f32 v8, v8, v9
	v_mul_f32_e32 v9, v10, v159
	v_mul_f32_e32 v4, v4, v159
	v_mul_f32_e32 v5, v5, v159
	v_mul_f32_e32 v10, v11, v159
	v_cvt_pk_bf16_f32 v9, v9, v10
	global_store_dwordx2 v[162:163], v[8:9], off offset:32
	v_cvt_pk_bf16_f32 v4, v4, v5
	v_mul_f32_e32 v5, v6, v159
	v_mul_f32_e32 v0, v0, v159
	v_mul_f32_e32 v1, v1, v159
	v_mul_f32_e32 v6, v7, v159
	v_cvt_pk_bf16_f32 v5, v5, v6
	global_store_dwordx2 v[162:163], v[4:5], off offset:64
	v_cvt_pk_bf16_f32 v0, v0, v1
	v_mul_f32_e32 v1, v2, v159
	v_mul_f32_e32 v2, v3, v159
	v_cvt_pk_bf16_f32 v1, v1, v2
	global_store_dwordx2 v[162:163], v[0:1], off offset:96
	v_mul_f32_e32 v0, v28, v159
	v_mul_f32_e32 v1, v29, v159
	v_cvt_pk_bf16_f32 v0, v0, v1
	v_mul_f32_e32 v1, v30, v159
	v_mul_f32_e32 v2, v31, v159
	v_cvt_pk_bf16_f32 v1, v1, v2
	global_store_dwordx2 v[162:163], v[0:1], off offset:128
	v_mul_f32_e32 v0, v20, v159
	v_mul_f32_e32 v1, v21, v159
	v_cvt_pk_bf16_f32 v0, v0, v1
	v_mul_f32_e32 v1, v22, v159
	v_mul_f32_e32 v2, v23, v159
	v_cvt_pk_bf16_f32 v1, v1, v2
	global_store_dwordx2 v[162:163], v[0:1], off offset:160
	v_mul_f32_e32 v0, v16, v159
	v_mul_f32_e32 v1, v17, v159
	v_cvt_pk_bf16_f32 v0, v0, v1
	v_mul_f32_e32 v1, v18, v159
	v_mul_f32_e32 v2, v19, v159
	v_cvt_pk_bf16_f32 v1, v1, v2
	global_store_dwordx2 v[162:163], v[0:1], off offset:192
	v_mul_f32_e32 v0, v12, v159
	v_mul_f32_e32 v1, v13, v159
	v_cvt_pk_bf16_f32 v0, v0, v1
	v_mul_f32_e32 v1, v14, v159
	v_mul_f32_e32 v2, v15, v159
	v_cvt_pk_bf16_f32 v1, v1, v2
	global_store_dwordx2 v[162:163], v[0:1], off offset:224
	v_mul_f32_e32 v0, v44, v159
	v_mul_f32_e32 v1, v45, v159
	v_cvt_pk_bf16_f32 v0, v0, v1
	v_mul_f32_e32 v1, v46, v159
	v_mul_f32_e32 v2, v47, v159
	v_cvt_pk_bf16_f32 v1, v1, v2
	global_store_dwordx2 v[162:163], v[0:1], off offset:256
	v_mul_f32_e32 v0, v40, v159
	v_mul_f32_e32 v1, v41, v159
	v_cvt_pk_bf16_f32 v0, v0, v1
	v_mul_f32_e32 v1, v42, v159
	v_mul_f32_e32 v2, v43, v159
	v_cvt_pk_bf16_f32 v1, v1, v2
	global_store_dwordx2 v[162:163], v[0:1], off offset:288
	v_mul_f32_e32 v0, v36, v159
	v_mul_f32_e32 v1, v37, v159
	v_cvt_pk_bf16_f32 v0, v0, v1
	v_mul_f32_e32 v1, v38, v159
	v_mul_f32_e32 v2, v39, v159
	v_cvt_pk_bf16_f32 v1, v1, v2
	global_store_dwordx2 v[162:163], v[0:1], off offset:320
	v_mul_f32_e32 v0, v32, v159
	v_mul_f32_e32 v1, v33, v159
	v_cvt_pk_bf16_f32 v0, v0, v1
	v_mul_f32_e32 v1, v34, v159
	v_mul_f32_e32 v2, v35, v159
	v_cvt_pk_bf16_f32 v1, v1, v2
	global_store_dwordx2 v[162:163], v[0:1], off offset:352
	v_mul_f32_e32 v0, v60, v159
	v_mul_f32_e32 v1, v61, v159
	v_cvt_pk_bf16_f32 v0, v0, v1
	v_mul_f32_e32 v1, v62, v159
	v_mul_f32_e32 v2, v63, v159
	v_cvt_pk_bf16_f32 v1, v1, v2
	global_store_dwordx2 v[162:163], v[0:1], off offset:384
	v_mul_f32_e32 v0, v56, v159
	v_mul_f32_e32 v1, v57, v159
	v_cvt_pk_bf16_f32 v0, v0, v1
	v_mul_f32_e32 v1, v58, v159
	v_mul_f32_e32 v2, v59, v159
	v_cvt_pk_bf16_f32 v1, v1, v2
	global_store_dwordx2 v[162:163], v[0:1], off offset:416
	v_mul_f32_e32 v0, v52, v159
	v_mul_f32_e32 v1, v53, v159
	v_cvt_pk_bf16_f32 v0, v0, v1
	v_mul_f32_e32 v1, v54, v159
	v_mul_f32_e32 v2, v55, v159
	v_cvt_pk_bf16_f32 v1, v1, v2
	global_store_dwordx2 v[162:163], v[0:1], off offset:448
	v_mul_f32_e32 v0, v48, v159
	v_mul_f32_e32 v1, v49, v159
	v_cvt_pk_bf16_f32 v0, v0, v1
	v_mul_f32_e32 v1, v50, v159
	v_mul_f32_e32 v2, v51, v159
	v_cvt_pk_bf16_f32 v1, v1, v2
	global_store_dwordx2 v[162:163], v[0:1], off offset:480
	s_cbranch_scc1 .LBB0_362
